# v25 + non-temporal hint on single-use chain loads (hgrn forget gates, gated-delta T tiles)
# baseline (speedup 1.0000x reference)
.LBB0_436:
	v_add_u32_e32 v105, s34, v85
	v_cvt_pk_bf16_f32 v48, v48, v49
	v_cvt_pk_bf16_f32 v49, v50, v51
	v_lshl_or_b32 v50, v105, 10, v52
	v_mov_b32_e32 v51, v53
	v_lshl_add_u64 v[50:51], v[50:51], 1, s[28:29]
	global_store_dwordx2 v[50:51], v[48:49], off offset:1024
	v_add_u32_e32 v48, s34, v86
	v_cvt_pk_bf16_f32 v44, v44, v45
	v_cvt_pk_bf16_f32 v45, v46, v47
	v_lshl_or_b32 v46, v48, 10, v52
	v_mov_b32_e32 v47, v53
	v_lshl_add_u64 v[46:47], v[46:47], 1, s[28:29]
	global_store_dwordx2 v[46:47], v[44:45], off offset:1024
	v_mov_b32_e32 v44, v68
	s_waitcnt vmcnt(5)
	v_lshlrev_b32_e32 v108, 16, v12
	v_ashrrev_i32_e32 v45, 3, v44
	v_lshlrev_b32_e32 v44, 4, v44
	v_mul_lo_u32 v105, v45, s61
	v_and_b32_e32 v116, 0x70, v44
	v_add3_u32 v117, 0, v105, v116
	v_lshl_add_u32 v44, v45, 2, 0
	ds_write_b128 v117, v[4:7]
	v_add_u32_e32 v44, 0x1fa00, v44
	ds_read_b32 v118, v44
	v_and_b32_e32 v109, 0xffff0000, v12
	v_and_b32_e32 v45, 0xffff0000, v8
	v_lshlrev_b32_e32 v110, 16, v13
	v_and_b32_e32 v111, 0xffff0000, v13
	s_waitcnt lgkmcnt(0)
	v_mul_f32_e32 v44, 0x3fb8aa3b, v118
	v_exp_f32_e32 v106, v44
	v_lshlrev_b32_e32 v44, 16, v8
	v_lshlrev_b32_e32 v114, 16, v11
	v_and_b32_e32 v115, 0xffff0000, v11
	v_pk_mul_f32 v[46:47], v[106:107], v[108:109] op_sel_hi:[0,1]
	v_cvt_pk_bf16_f32 v48, v46, v47
	v_lshlrev_b32_e32 v46, 16, v9
	v_and_b32_e32 v47, 0xffff0000, v9
	v_pk_mul_f32 v[44:45], v[106:107], v[44:45] op_sel_hi:[0,1]
	v_pk_mul_f32 v[46:47], v[106:107], v[46:47] op_sel_hi:[0,1]
	v_cvt_pk_bf16_f32 v44, v44, v45
	v_cvt_pk_bf16_f32 v45, v46, v47
	v_pk_mul_f32 v[46:47], v[106:107], v[110:111] op_sel_hi:[0,1]
	v_cvt_pk_bf16_f32 v49, v46, v47
	v_lshlrev_b32_e32 v46, 16, v10
	v_and_b32_e32 v47, 0xffff0000, v10
	v_pk_mul_f32 v[46:47], v[106:107], v[46:47] op_sel_hi:[0,1]
	v_pk_mul_f32 v[114:115], v[106:107], v[114:115] op_sel_hi:[0,1]
	v_cvt_pk_bf16_f32 v46, v46, v47
	v_lshlrev_b32_e32 v112, 16, v14
	v_and_b32_e32 v113, 0xffff0000, v14
	v_cvt_pk_bf16_f32 v47, v114, v115
	v_lshlrev_b32_e32 v114, 16, v15
	v_and_b32_e32 v115, 0xffff0000, v15
	v_pk_mul_f32 v[50:51], v[106:107], v[112:113] op_sel_hi:[0,1]
	v_pk_mul_f32 v[106:107], v[106:107], v[114:115] op_sel_hi:[0,1]
	v_readlane_b32 s4, v255, 4
	v_cvt_pk_bf16_f32 v50, v50, v51
	v_cvt_pk_bf16_f32 v51, v106, v107
	v_add3_u32 v106, s4, v105, v116
	ds_write_b128 v106, v[44:47]
	ds_write_b128 v117, v[48:51] offset:18432
	v_add3_u32 v44, s40, v105, v116
	ds_write_b128 v44, v[8:11]
	v_add3_u32 v44, s41, v105, v116
	ds_write_b128 v44, v[12:15]
	s_waitcnt vmcnt(4)
	ds_write_b128 v117, v[16:19] offset:46080
	v_mov_b32_e32 v44, s72
	ds_read_b32 v44, v44
	v_readlane_b32 s4, v255, 6
	s_cmp_gt_u32 s45, 64
	s_waitcnt lgkmcnt(0)
	v_sub_f32_e32 v44, v44, v118
	v_mul_f32_e32 v44, 0x3fb8aa3b, v44
	v_exp_f32_e32 v48, v44
	s_nop 0
	v_pk_mul_f32 v[44:45], v[48:49], v[108:109] op_sel_hi:[0,1]
	v_pk_mul_f32 v[46:47], v[48:49], v[110:111] op_sel_hi:[0,1]
	v_cvt_pk_bf16_f32 v44, v44, v45
	v_cvt_pk_bf16_f32 v45, v46, v47
	v_pk_mul_f32 v[46:47], v[48:49], v[112:113] op_sel_hi:[0,1]
	v_pk_mul_f32 v[48:49], v[48:49], v[114:115] op_sel_hi:[0,1]
	v_cvt_pk_bf16_f32 v46, v46, v47
	v_cvt_pk_bf16_f32 v47, v48, v49
	v_add3_u32 v48, s4, v105, v116
	ds_write_b128 v48, v[44:47]
	s_waitcnt lgkmcnt(0)
	s_barrier
	s_cbranch_scc1 .Lgdn_skipA
	s_and_b64 s[4:5], s[26:27], exec
	s_cselect_b32 s4, s43, s44
	s_lshl_b32 s35, s4, 6
	s_add_i32 s35, s35, s2
	s_add_i32 s34, s33, 64
	v_mov_b32_e32 v4, v68
	s_and_b64 s[4:5], s[26:27], exec
	s_cselect_b32 s34, s42, s34
	v_ashrrev_i32_e32 v6, 3, v4
	s_add_i32 s34, s34, s1
	v_add_u32_e32 v5, s35, v6
	v_lshlrev_b32_e32 v4, 3, v4
	v_mul_lo_u32 v6, v6, s39
	v_and_b32_e32 v7, 56, v4
	v_add_u32_e32 v6, s34, v6
	v_or_b32_e32 v4, s0, v7
	v_mul_u32_u24_e32 v6, 0x300, v6
	v_mad_u32_u24 v4, v5, s63, v4
	v_or3_b32 v6, v6, s37, v7
	v_ashrrev_i32_e32 v5, 31, v4
	v_ashrrev_i32_e32 v7, 31, v6
	v_lshl_add_u64 v[4:5], v[4:5], 1, s[82:83]
	v_lshl_add_u64 v[16:17], v[6:7], 1, s[84:85]
	global_load_dwordx4 v[4:7], v[4:5], off nt
	s_nop 0
	global_load_dwordx4 v[8:11], v[16:17], off
	global_load_dwordx4 v[12:15], v[16:17], off offset:512
	s_nop 0
	global_load_dwordx4 v[16:19], v[16:17], off offset:1024
	s_and_saveexec_b64 s[4:5], s[6:7]
	s_cbranch_execz .LBB0_439
	v_add_u32_e32 v44, s35, v68
	v_lshl_add_u32 v180, v44, 4, v59
	v_lshl_add_u64 v[44:45], v[180:181], 2, s[86:87]
	global_load_dword v55, v[44:45], off
	v_add_u32_e32 v44, s34, v54
	v_lshl_add_u32 v180, v44, 4, v89
	v_lshl_add_u64 v[44:45], v[180:181], 2, s[86:87]
	global_load_dword v58, v[44:45], off

.LBB0_450:
	s_cmp_gt_u32 s48, 64
	s_waitcnt lgkmcnt(0)
	s_barrier
	s_cbranch_scc1 .Lgdn_skipB
	s_add_i32 s30, s43, 1
	s_add_i32 s31, s44, -1
	s_and_b64 s[4:5], s[26:27], exec
	s_cselect_b32 s4, s30, s31
	s_lshl_b32 s31, s4, 6
	s_add_i32 s31, s31, s2
	s_waitcnt vmcnt(7)
	v_mov_b32_e32 v20, v68
	s_and_b64 s[4:5], s[26:27], exec
	s_cselect_b32 s30, s47, s33
	v_ashrrev_i32_e32 v22, 3, v20
	s_add_i32 s30, s30, s1
	v_add_u32_e32 v21, s31, v22
	v_lshlrev_b32_e32 v20, 3, v20
	v_mul_lo_u32 v22, v22, s39
	v_and_b32_e32 v23, 56, v20
	v_add_u32_e32 v22, s30, v22
	v_or_b32_e32 v20, s0, v23
	v_mul_u32_u24_e32 v22, 0x300, v22
	v_mad_u32_u24 v20, v21, s63, v20
	v_or3_b32 v22, v22, s37, v23
	v_ashrrev_i32_e32 v21, 31, v20
	v_ashrrev_i32_e32 v23, 31, v22
	v_lshl_add_u64 v[20:21], v[20:21], 1, s[82:83]
	s_waitcnt vmcnt(4)
	v_lshl_add_u64 v[32:33], v[22:23], 1, s[84:85]
	global_load_dwordx4 v[20:23], v[20:21], off nt
	s_nop 0
	global_load_dwordx4 v[24:27], v[32:33], off
	global_load_dwordx4 v[28:31], v[32:33], off offset:512
	s_nop 0
	global_load_dwordx4 v[32:35], v[32:33], off offset:1024
	s_and_saveexec_b64 s[4:5], s[6:7]
	s_cbranch_execz .LBB0_426
	v_add_u32_e32 v44, s31, v68
	v_lshl_add_u32 v180, v44, 4, v59
	v_lshl_add_u64 v[44:45], v[180:181], 2, s[86:87]
	global_load_dword v56, v[44:45], off
	v_add_u32_e32 v44, s30, v54
	v_lshl_add_u32 v180, v44, 4, v89
	v_lshl_add_u64 v[44:45], v[180:181], 2, s[86:87]
	global_load_dword v57, v[44:45], off
	s_branch .LBB0_426

.LBB0_488:
	v_mov_b32_e32 v36, v68
	s_cmpk_lt_u32 s47, 0x42
	v_lshrrev_b32_e32 v37, 3, v36
	v_and_or_b32 v37, v37, 7, s70
	v_lshlrev_b32_e32 v36, 4, v36
	s_cselect_b64 s[54:55], -1, 0
	s_cmpk_gt_u32 s47, 0x41
	v_mul_lo_u32 v37, v37, s61
	v_and_b32_e32 v36, 0x70, v36
	v_readlane_b32 s4, v255, 7
	s_cselect_b64 s[60:61], -1, 0
	s_movk_i32 s72, 0x90
	v_add3_u32 v36, s4, v37, v36
	s_and_b64 vcc, exec, s[60:61]
	s_waitcnt vmcnt(5)
	ds_write_b128 v36, v[20:23]
	s_waitcnt lgkmcnt(0)
	s_barrier
	s_cbranch_vccnz .Lhg_skipA
	s_lshl_b32 s4, s47, 6
	s_add_i32 s36, s4, 0xffffff80
	s_sub_i32 s37, 0x107f, s4
	v_mov_b32_e32 v4, v68
	s_and_b64 s[4:5], s[6:7], exec
	s_cselect_b32 s4, s36, s37
	v_lshrrev_b32_e32 v5, 3, v4
	s_add_i32 s4, s4, s76
	v_and_or_b32 v5, v5, 7, s70
	s_cmp_eq_u32 s47, 0
	v_sub_u32_e32 v6, 0, v5
	s_cselect_b32 s4, s2, s4
	v_cndmask_b32_e64 v5, v6, v5, s[6:7]
	v_add_u32_e32 v5, s4, v5
	s_and_b64 s[4:5], s[6:7], exec
	s_cselect_b32 s5, 0, -1
	s_mov_b32 s4, 0x70000
	s_xor_b32 s4, s4, s5
	s_sub_u32 s4, s4, s5
	v_mul_u32_u24_e32 v5, 0xe00, v5
	v_lshlrev_b32_e32 v4, 3, v4
	v_and_or_b32 v4, v4, 56, v5
	v_ashrrev_i32_e32 v5, 31, v4
	v_lshl_add_u64 v[12:13], v[4:5], 1, s[58:59]
	s_lshl_b32 s48, s73, 1
	v_lshl_add_u64 v[4:5], v[12:13], 0, s[48:49]
	v_lshl_add_u64 v[176:177], v[4:5], 0, s[4:5]
	global_load_dwordx4 v[4:7], v[4:5], off offset:1536 nt
	s_nop 0
	global_load_dwordx4 v[8:11], v[12:13], off
	s_nop 0
	global_load_dwordx4 v[12:15], v[12:13], off offset:512
	global_load_dword v178, v[176:177], off offset:1536

.LBB0_517:
	s_andn2_b64 vcc, exec, s[54:55]
	s_waitcnt lgkmcnt(0)
	s_barrier
	s_cbranch_vccnz .Lhg_skipB
	s_lshl_b32 s4, s40, 6
	s_add_i32 s41, s4, 0xffffff80
	s_sub_i32 s48, 0x107f, s4
	v_mov_b32_e32 v16, v68
	s_and_b64 s[4:5], s[6:7], exec
	s_cselect_b32 s4, s41, s48
	v_lshrrev_b32_e32 v17, 3, v16
	s_add_i32 s4, s4, s76
	v_and_or_b32 v17, v17, 7, s70
	s_cmp_eq_u32 s47, 0
	v_sub_u32_e32 v18, 0, v17
	s_cselect_b32 s4, s74, s4
	v_cndmask_b32_e64 v17, v18, v17, s[6:7]
	v_add_u32_e32 v17, s4, v17
	s_and_b64 s[4:5], s[6:7], exec
	s_cselect_b32 s5, 0, -1
	s_mov_b32 s4, 0x70000
	s_xor_b32 s4, s4, s5
	s_sub_u32 s4, s4, s5
	v_mul_u32_u24_e32 v17, 0xe00, v17
	v_lshlrev_b32_e32 v16, 3, v16
	v_and_or_b32 v16, v16, 56, v17
	v_ashrrev_i32_e32 v17, 31, v16
	v_lshl_add_u64 v[24:25], v[16:17], 1, s[58:59]
	s_lshl_b32 s48, s73, 1
	v_lshl_add_u64 v[16:17], v[24:25], 0, s[48:49]
	v_lshl_add_u64 v[176:177], v[16:17], 0, s[4:5]
	global_load_dwordx4 v[20:23], v[16:17], off offset:1536 nt
	s_nop 0
	global_load_dwordx4 v[16:19], v[24:25], off
	s_nop 0
	global_load_dwordx4 v[24:27], v[24:25], off offset:512
	global_load_dword v178, v[176:177], off offset:1536
